# final candidate: no s_setprio in GEMM K-loops, batched loads in PEER fold staging / sample-row GEMM tiles / first-barrier census, spatial bias loads hoisted
# baseline (speedup 1.0000x reference)
.LBB0_859:
	v_readlane_b32 s16, v253, 8
	v_readlane_b32 s17, v253, 9
	s_mov_b64 s[12:13], -1
	s_nop 4
	global_load_dword v0, v145, s[16:17] sc1
	global_load_dword v1, v145, s[16:17] offset:256 sc1
	global_load_dword v2, v145, s[16:17] offset:512 sc1
	global_load_dword v3, v145, s[16:17] offset:768 sc1
	global_load_dword v4, v145, s[16:17] offset:1024 sc1
	global_load_dword v5, v145, s[16:17] offset:1280 sc1
	global_load_dword v6, v145, s[16:17] offset:1536 sc1
	global_load_dword v7, v145, s[16:17] offset:1792 sc1
	global_load_dword v8, v145, s[16:17] offset:2048 sc1
	global_load_dword v9, v145, s[16:17] offset:2304 sc1
	global_load_dword v10, v145, s[16:17] offset:2560 sc1
	global_load_dword v11, v145, s[16:17] offset:2816 sc1
	global_load_dword v12, v145, s[16:17] offset:3072 sc1
	global_load_dword v13, v145, s[16:17] offset:3328 sc1
	global_load_dword v14, v145, s[16:17] offset:3584 sc1
	global_load_dword v15, v145, s[16:17] offset:3840 sc1
	s_mov_b64 s[4:5], -1
	s_waitcnt vmcnt(0)
	v_add_u32_e32 v16, v1, v0
	v_add_u32_e32 v16, v16, v2
	v_add_u32_e32 v16, v16, v3
	v_add_u32_e32 v16, v16, v4
	v_add_u32_e32 v16, v16, v5
	v_add_u32_e32 v16, v16, v6
	v_add_u32_e32 v16, v16, v7
	v_add_u32_e32 v16, v16, v8
	v_add_u32_e32 v16, v16, v9
	v_add_u32_e32 v16, v16, v10
	v_add_u32_e32 v16, v16, v11
	v_add_u32_e32 v16, v16, v12
	v_add_u32_e32 v16, v16, v13
	v_add_u32_e32 v16, v16, v14
	v_add_u32_e32 v16, v16, v15
	v_cmp_eq_u32_e32 vcc, s15, v16
	s_cbranch_vccnz .LBB0_858
	s_and_b32 s4, s24, 0xff
	s_cmp_eq_u32 s4, 0
	s_mov_b64 s[4:5], -1
	s_mov_b64 s[16:17], -1
	s_sleep 1
	s_cbranch_scc0 .LBB0_863
	v_readlane_b32 s4, v253, 6
	v_readlane_b32 s5, v253, 7
	s_nop 4
	global_load_dword v16, v145, s[4:5] sc1
	s_waitcnt vmcnt(0)
	v_cmp_eq_u32_e32 vcc, 0, v16
	s_cbranch_vccnz .LBB0_865
	s_mov_b64 s[16:17], 0
	s_mov_b64 s[4:5], -1
